# operand warm-up: at the seams before P5 and P7, wave 2 touches its 64 KiB share of the phase's B matrix (w_conv_out / w_o) into L2, stacked on v93
# speedup vs baseline: 1.0013x; 1.0013x over previous
.Lcpf_skip_3:
	v_readlane_b32 s98, v254, 61
	s_cmp_lg_u32 s98, 2
	s_cbranch_scc1 .Lcpf_skip_b0
	v_readlane_b32 s98, v255, 6
	s_lshr_b32 s98, s98, 3
	s_lshl_b32 s98, s98, 16
	s_add_u32 s98, s98, 0x2980000
	s_add_u32 s98, s70, s98
	s_addc_u32 s99, s71, 0
	v_lshlrev_b32_e32 v252, 7, v186
	global_load_dword v253, v252, s[98:99]
	s_add_u32 s98, s98, 0x2000
	s_addc_u32 s99, s99, 0
	global_load_dword v253, v252, s[98:99]
	s_add_u32 s98, s98, 0x2000
	s_addc_u32 s99, s99, 0
	global_load_dword v253, v252, s[98:99]
	s_add_u32 s98, s98, 0x2000
	s_addc_u32 s99, s99, 0
	global_load_dword v253, v252, s[98:99]
	s_add_u32 s98, s98, 0x2000
	s_addc_u32 s99, s99, 0
	global_load_dword v253, v252, s[98:99]
	s_add_u32 s98, s98, 0x2000
	s_addc_u32 s99, s99, 0
	global_load_dword v253, v252, s[98:99]
	s_add_u32 s98, s98, 0x2000
	s_addc_u32 s99, s99, 0
	global_load_dword v253, v252, s[98:99]
	s_add_u32 s98, s98, 0x2000
	s_addc_u32 s99, s99, 0
	global_load_dword v253, v252, s[98:99]

.Lcpf_skip_5:
	v_readlane_b32 s98, v254, 61
	s_cmp_lg_u32 s98, 2
	s_cbranch_scc1 .Lcpf_skip_b1
	v_readlane_b32 s98, v255, 6
	s_lshr_b32 s98, s98, 3
	s_lshl_b32 s98, s98, 16
	s_add_u32 s98, s98, 0x2f80000
	s_add_u32 s98, s70, s98
	s_addc_u32 s99, s71, 0
	v_lshlrev_b32_e32 v252, 7, v186
	global_load_dword v253, v252, s[98:99]
	s_add_u32 s98, s98, 0x2000
	s_addc_u32 s99, s99, 0
	global_load_dword v253, v252, s[98:99]
	s_add_u32 s98, s98, 0x2000
	s_addc_u32 s99, s99, 0
	global_load_dword v253, v252, s[98:99]
	s_add_u32 s98, s98, 0x2000
	s_addc_u32 s99, s99, 0
	global_load_dword v253, v252, s[98:99]
	s_add_u32 s98, s98, 0x2000
	s_addc_u32 s99, s99, 0
	global_load_dword v253, v252, s[98:99]
	s_add_u32 s98, s98, 0x2000
	s_addc_u32 s99, s99, 0
	global_load_dword v253, v252, s[98:99]
	s_add_u32 s98, s98, 0x2000
	s_addc_u32 s99, s99, 0
	global_load_dword v253, v252, s[98:99]
	s_add_u32 s98, s98, 0x2000
	s_addc_u32 s99, s99, 0
	global_load_dword v253, v252, s[98:99]
